# leading half takes its ALIGN_EPI barrier one epilogue block into its epilogue (first block overlaps the trailing half's last MFMA phase)
# speedup vs baseline: 1.0008x; 1.0008x over previous
.LBB0_145:
.LBB0_147:
	s_waitcnt vmcnt(16)
	v_pk_mul_f32 v[128:129], v[120:121], v[128:129]
	v_alignbit_b32 v0, v131, v130, 24
	v_and_b32_e32 v147, 0xffffff, v130
	v_cvt_f32_u32_e32 v0, v0
	v_cvt_f32_u32_e32 v147, v147
	v_and_b32_e32 v148, 0xffffff, v144
	v_cvt_f32_u32_e32 v148, v148
	v_lshl_or_b32 v150, s53, 7, v160
	v_fmac_f32_e32 v0, 0x33800000, v147
	v_fmamk_f32 v0, v0, 0x3a000000, v200
	v_rsq_f32_e32 v167, v0
	v_alignbit_b32 v0, v133, v132, 24
	v_and_b32_e32 v147, 0xffffff, v132
	v_cvt_f32_u32_e32 v0, v0
	v_cvt_f32_u32_e32 v147, v147
	v_mul_f32_e32 v172, 0xbfb8aa3b, v167
	v_pk_mul_f32 v[174:175], v[118:119], v[172:173] op_sel_hi:[1,0]
	v_mul_f32_e32 v170, v167, v167
	v_fmac_f32_e32 v0, 0x33800000, v147
	v_fmamk_f32 v0, v0, 0x3a000000, v200
	v_rsq_f32_e32 v171, v0
	v_alignbit_b32 v0, v135, v134, 24
	v_and_b32_e32 v147, 0xffffff, v134
	v_cvt_f32_u32_e32 v0, v0
	v_cvt_f32_u32_e32 v147, v147
	v_exp_f32_e32 v174, v174
	v_exp_f32_e32 v175, v175
	v_pk_mul_f32 v[118:119], v[118:119], v[126:127]
	v_fmac_f32_e32 v0, 0x33800000, v147
	v_fmamk_f32 v0, v0, 0x3a000000, v200
	v_rsq_f32_e32 v166, v0
	v_alignbit_b32 v0, v137, v136, 24
	v_and_b32_e32 v147, 0xffffff, v136
	v_cvt_f32_u32_e32 v0, v0
	v_cvt_f32_u32_e32 v147, v147
	v_pk_add_f32 v[174:175], v[174:175], 1.0 op_sel_hi:[1,0]
	v_pk_mul_f32 v[120:121], v[120:121], v[172:173] op_sel_hi:[1,0]
	v_rcp_f32_e32 v174, v174
	v_fmac_f32_e32 v0, 0x33800000, v147
	v_fmamk_f32 v0, v0, 0x3a000000, v200
	v_rsq_f32_e32 v165, v0
	v_alignbit_b32 v0, v139, v138, 24
	v_and_b32_e32 v147, 0xffffff, v138
	v_rcp_f32_e32 v175, v175
	v_cvt_f32_u32_e32 v0, v0
	v_cvt_f32_u32_e32 v147, v147
	v_exp_f32_e32 v120, v120
	v_pk_mul_f32 v[126:127], v[170:171], v[174:175] op_sel_hi:[0,1]
	v_pk_mul_f32 v[118:119], v[118:119], v[126:127]
	v_fmac_f32_e32 v0, 0x33800000, v147
	v_pk_mul_f32 v[126:127], v[110:111], v[172:173] op_sel_hi:[1,0]
	v_fmamk_f32 v0, v0, 0x3a000000, v200
	v_exp_f32_e32 v126, v126
	v_exp_f32_e32 v127, v127
	v_rsq_f32_e32 v164, v0
	v_alignbit_b32 v0, v141, v140, 24
	v_and_b32_e32 v147, 0xffffff, v140
	v_cvt_f32_u32_e32 v0, v0
	v_cvt_f32_u32_e32 v147, v147
	v_pk_add_f32 v[126:127], v[126:127], 1.0 op_sel_hi:[1,0]
	v_pk_mul_f32 v[110:111], v[110:111], v[122:123]
	v_rcp_f32_e32 v126, v126
	v_rcp_f32_e32 v127, v127
	v_fmac_f32_e32 v0, 0x33800000, v147
	v_fmamk_f32 v0, v0, 0x3a000000, v200
	v_rsq_f32_e32 v163, v0
	v_alignbit_b32 v0, v143, v142, 24
	v_and_b32_e32 v147, 0xffffff, v142
	v_cvt_f32_u32_e32 v0, v0
	v_cvt_f32_u32_e32 v147, v147
	v_pk_mul_f32 v[122:123], v[170:171], v[126:127] op_sel_hi:[0,1]
	v_pk_mul_f32 v[122:123], v[110:111], v[122:123]
	v_pk_mul_f32 v[110:111], v[112:113], v[172:173] op_sel_hi:[1,0]
	v_exp_f32_e32 v121, v121
	v_exp_f32_e32 v110, v110
	v_exp_f32_e32 v111, v111
	v_fmac_f32_e32 v0, 0x33800000, v147
	v_fmamk_f32 v0, v0, 0x3a000000, v200
	v_rsq_f32_e32 v147, v0
	v_alignbit_b32 v0, v145, v144, 24
	v_pk_add_f32 v[120:121], v[120:121], 1.0 op_sel_hi:[1,0]
	v_pk_add_f32 v[110:111], v[110:111], 1.0 op_sel_hi:[1,0]
	v_cvt_f32_u32_e32 v0, v0
	v_rcp_f32_e32 v120, v120
	v_rcp_f32_e32 v121, v121
	v_rcp_f32_e32 v110, v110
	v_rcp_f32_e32 v111, v111
	v_fmac_f32_e32 v0, 0x33800000, v148
	v_ashrrev_i32_e32 v151, 31, v150
	v_mov_b64_e32 v[148:149], s[16:17]
	v_pk_mul_f32 v[120:121], v[170:171], v[120:121] op_sel_hi:[0,1]
	v_pk_mul_f32 v[124:125], v[112:113], v[124:125]
	v_pk_mul_f32 v[110:111], v[170:171], v[110:111] op_sel_hi:[0,1]
	v_mad_i64_i32 v[168:169], s[10:11], v146, s99, v[148:149]
	v_pk_mul_f32 v[120:121], v[128:129], v[120:121]
	v_pk_mul_f32 v[112:113], v[124:125], v[110:111]
	v_lshlrev_b64 v[110:111], 1, v[150:151]
	v_lshl_add_u64 v[124:125], v[168:169], 0, v[110:111]
	v_cvt_pk_bf16_f32 v118, v118, v119
	v_cvt_pk_bf16_f32 v119, v120, v121
	v_cvt_pk_bf16_f32 v120, v122, v123
	v_cvt_pk_bf16_f32 v121, v112, v113
	global_store_dwordx4 v[124:125], v[118:121], off
	s_and_b64 vcc, exec, s[20:21]
	s_cbranch_vccz .Lpepi_s
	s_barrier
.Lpepi_s:
	v_pk_mul_f32 v[116:117], v[104:105], v[116:117]
	v_pk_mul_f32 v[108:109], v[96:97], v[108:109]
	v_mul_f32_e32 v120, 0xbfb8aa3b, v171
	v_pk_mul_f32 v[122:123], v[102:103], v[120:121] op_sel_hi:[1,0]
	v_mul_f32_e32 v118, v171, v171
	v_exp_f32_e32 v122, v122
	v_exp_f32_e32 v123, v123
	v_pk_mul_f32 v[102:103], v[102:103], v[114:115]
	v_pk_mul_f32 v[104:105], v[104:105], v[120:121] op_sel_hi:[1,0]
	v_or_b32_e32 v112, 16, v146
	v_pk_add_f32 v[122:123], v[122:123], 1.0 op_sel_hi:[1,0]
	v_exp_f32_e32 v104, v104
	v_rcp_f32_e32 v122, v122
	v_rcp_f32_e32 v123, v123
	v_exp_f32_e32 v105, v105
	v_mad_i64_i32 v[112:113], s[10:11], v112, s99, v[148:149]
	v_pk_mul_f32 v[114:115], v[118:119], v[122:123] op_sel_hi:[0,1]
	v_pk_mul_f32 v[102:103], v[102:103], v[114:115]
	v_pk_mul_f32 v[114:115], v[94:95], v[120:121] op_sel_hi:[1,0]
	v_pk_mul_f32 v[94:95], v[94:95], v[106:107]
	v_exp_f32_e32 v114, v114
	v_exp_f32_e32 v115, v115
	v_pk_add_f32 v[104:105], v[104:105], 1.0 op_sel_hi:[1,0]
	v_lshl_add_u64 v[112:113], v[112:113], 0, v[110:111]
	v_rcp_f32_e32 v104, v104
	v_pk_add_f32 v[114:115], v[114:115], 1.0 op_sel_hi:[1,0]
	v_rcp_f32_e32 v105, v105
	v_rcp_f32_e32 v114, v114
	v_rcp_f32_e32 v115, v115
	v_pk_mul_f32 v[100:101], v[88:89], v[100:101]
	v_pk_mul_f32 v[104:105], v[118:119], v[104:105] op_sel_hi:[0,1]
	v_pk_mul_f32 v[104:105], v[116:117], v[104:105]
	v_pk_mul_f32 v[106:107], v[118:119], v[114:115] op_sel_hi:[0,1]
	v_pk_mul_f32 v[106:107], v[94:95], v[106:107]
	v_pk_mul_f32 v[94:95], v[96:97], v[120:121] op_sel_hi:[1,0]
	v_pk_mul_f32 v[92:93], v[80:81], v[92:93]
	v_exp_f32_e32 v94, v94
	v_exp_f32_e32 v95, v95
	v_pk_mul_f32 v[84:85], v[68:69], v[84:85]
	v_pk_mul_f32 v[76:77], v[60:61], v[76:77]
	v_pk_mul_f32 v[72:73], v[56:57], v[72:73]
	v_pk_add_f32 v[94:95], v[94:95], 1.0 op_sel_hi:[1,0]
	v_pk_mul_f32 v[64:65], v[48:49], v[64:65]
	v_rcp_f32_e32 v94, v94
	v_rcp_f32_e32 v95, v95
	v_pk_mul_f32 v[52:53], v[40:41], v[52:53]
	v_pk_mul_f32 v[44:45], v[32:33], v[44:45]
	v_pk_mul_f32 v[36:37], v[24:25], v[36:37]
	v_pk_mul_f32 v[94:95], v[118:119], v[94:95] op_sel_hi:[0,1]
	v_pk_mul_f32 v[108:109], v[108:109], v[94:95]
	v_cvt_pk_bf16_f32 v94, v102, v103
	v_mul_f32_e32 v102, 0xbfb8aa3b, v166
	v_cvt_pk_bf16_f32 v95, v104, v105
	v_pk_mul_f32 v[104:105], v[86:87], v[102:103] op_sel_hi:[1,0]
	v_cvt_pk_bf16_f32 v96, v106, v107
	v_cvt_pk_bf16_f32 v97, v108, v109
	global_store_dwordx4 v[112:113], v[94:97], off
	v_exp_f32_e32 v104, v104
	v_exp_f32_e32 v105, v105
	v_mul_f32_e32 v96, v166, v166
	v_pk_mul_f32 v[86:87], v[86:87], v[98:99]
	v_pk_mul_f32 v[88:89], v[88:89], v[102:103] op_sel_hi:[1,0]
	v_pk_add_f32 v[104:105], v[104:105], 1.0 op_sel_hi:[1,0]
	v_exp_f32_e32 v88, v88
	v_rcp_f32_e32 v104, v104
	v_rcp_f32_e32 v105, v105
	v_exp_f32_e32 v89, v89
	v_or_b32_e32 v94, 32, v146
	v_mad_i64_i32 v[94:95], s[10:11], v94, s99, v[148:149]
	v_pk_mul_f32 v[98:99], v[96:97], v[104:105] op_sel_hi:[0,1]
	v_pk_mul_f32 v[86:87], v[86:87], v[98:99]
	v_pk_mul_f32 v[98:99], v[78:79], v[102:103] op_sel_hi:[1,0]
	v_pk_mul_f32 v[78:79], v[78:79], v[90:91]
	v_exp_f32_e32 v98, v98
	v_exp_f32_e32 v99, v99
	v_pk_add_f32 v[88:89], v[88:89], 1.0 op_sel_hi:[1,0]
	v_lshl_add_u64 v[94:95], v[94:95], 0, v[110:111]
	v_rcp_f32_e32 v88, v88
	v_pk_add_f32 v[98:99], v[98:99], 1.0 op_sel_hi:[1,0]
	v_rcp_f32_e32 v89, v89
	v_rcp_f32_e32 v98, v98
	v_rcp_f32_e32 v99, v99
	v_fmamk_f32 v0, v0, 0x3a000000, v200
	v_pk_mul_f32 v[88:89], v[96:97], v[88:89] op_sel_hi:[0,1]
	v_pk_mul_f32 v[88:89], v[100:101], v[88:89]
	v_pk_mul_f32 v[90:91], v[96:97], v[98:99] op_sel_hi:[0,1]
	v_pk_mul_f32 v[90:91], v[78:79], v[90:91]
	v_pk_mul_f32 v[78:79], v[80:81], v[102:103] op_sel_hi:[1,0]
	v_rsq_f32_e32 v0, v0
	v_exp_f32_e32 v78, v78
	v_exp_f32_e32 v79, v79
	v_pk_mul_f32 v[28:29], v[16:17], v[28:29]
	v_pk_mul_f32 v[20:21], v[8:9], v[20:21]
	v_pk_mul_f32 v[12:13], v[4:5], v[12:13]
	v_pk_add_f32 v[78:79], v[78:79], 1.0 op_sel_hi:[1,0]
	s_andn2_b64 vcc, exec, s[4:5]
	v_rcp_f32_e32 v78, v78
	v_rcp_f32_e32 v79, v79
	s_nop 0
	v_pk_mul_f32 v[78:79], v[96:97], v[78:79] op_sel_hi:[0,1]
	v_pk_mul_f32 v[92:93], v[92:93], v[78:79]
	v_cvt_pk_bf16_f32 v78, v86, v87
	v_mul_f32_e32 v86, 0xbfb8aa3b, v165
	v_cvt_pk_bf16_f32 v79, v88, v89
	v_pk_mul_f32 v[88:89], v[66:67], v[86:87] op_sel_hi:[1,0]
	v_cvt_pk_bf16_f32 v80, v90, v91
	v_cvt_pk_bf16_f32 v81, v92, v93
	global_store_dwordx4 v[94:95], v[78:81], off
	v_exp_f32_e32 v88, v88
	v_exp_f32_e32 v89, v89
	v_mul_f32_e32 v80, v165, v165
	v_pk_mul_f32 v[66:67], v[66:67], v[82:83]
	v_pk_mul_f32 v[68:69], v[68:69], v[86:87] op_sel_hi:[1,0]
	v_pk_add_f32 v[88:89], v[88:89], 1.0 op_sel_hi:[1,0]
	v_exp_f32_e32 v68, v68
	v_rcp_f32_e32 v88, v88
	v_rcp_f32_e32 v89, v89
	v_exp_f32_e32 v69, v69
	v_or_b32_e32 v78, 48, v146
	v_mad_i64_i32 v[78:79], s[10:11], v78, s99, v[148:149]
	v_pk_mul_f32 v[82:83], v[80:81], v[88:89] op_sel_hi:[0,1]
	v_pk_mul_f32 v[66:67], v[66:67], v[82:83]
	v_pk_mul_f32 v[82:83], v[58:59], v[86:87] op_sel_hi:[1,0]
	v_pk_mul_f32 v[58:59], v[58:59], v[74:75]
	v_exp_f32_e32 v82, v82
	v_exp_f32_e32 v83, v83
	v_pk_add_f32 v[68:69], v[68:69], 1.0 op_sel_hi:[1,0]
	v_lshl_add_u64 v[78:79], v[78:79], 0, v[110:111]
	v_rcp_f32_e32 v68, v68
	v_pk_add_f32 v[82:83], v[82:83], 1.0 op_sel_hi:[1,0]
	v_rcp_f32_e32 v69, v69
	v_rcp_f32_e32 v82, v82
	v_rcp_f32_e32 v83, v83
	v_pk_mul_f32 v[68:69], v[80:81], v[68:69] op_sel_hi:[0,1]
	v_pk_mul_f32 v[68:69], v[84:85], v[68:69]
	v_pk_mul_f32 v[74:75], v[80:81], v[82:83] op_sel_hi:[0,1]
	v_pk_mul_f32 v[74:75], v[58:59], v[74:75]
	v_pk_mul_f32 v[58:59], v[60:61], v[86:87] op_sel_hi:[1,0]
	s_nop 0
	v_exp_f32_e32 v58, v58
	v_exp_f32_e32 v59, v59
	s_nop 0
	v_pk_add_f32 v[58:59], v[58:59], 1.0 op_sel_hi:[1,0]
	s_nop 0
	v_rcp_f32_e32 v58, v58
	v_rcp_f32_e32 v59, v59
	s_nop 0
	v_pk_mul_f32 v[58:59], v[80:81], v[58:59] op_sel_hi:[0,1]
	v_pk_mul_f32 v[76:77], v[76:77], v[58:59]
	v_cvt_pk_bf16_f32 v58, v66, v67
	v_mul_f32_e32 v66, 0xbfb8aa3b, v164
	v_cvt_pk_bf16_f32 v59, v68, v69
	v_pk_mul_f32 v[68:69], v[54:55], v[66:67] op_sel_hi:[1,0]
	v_cvt_pk_bf16_f32 v60, v74, v75
	v_cvt_pk_bf16_f32 v61, v76, v77
	global_store_dwordx4 v[78:79], v[58:61], off
	v_exp_f32_e32 v68, v68
	v_exp_f32_e32 v69, v69
	v_mul_f32_e32 v60, v164, v164
	v_pk_mul_f32 v[54:55], v[54:55], v[70:71]
	v_pk_mul_f32 v[56:57], v[56:57], v[66:67] op_sel_hi:[1,0]
	v_pk_add_f32 v[68:69], v[68:69], 1.0 op_sel_hi:[1,0]
	v_exp_f32_e32 v56, v56
	v_rcp_f32_e32 v68, v68
	v_rcp_f32_e32 v69, v69
	v_exp_f32_e32 v57, v57
	v_add_u32_e32 v58, 0x80, v146
	v_mad_i64_i32 v[58:59], s[10:11], v58, s99, v[148:149]
	v_pk_mul_f32 v[68:69], v[60:61], v[68:69] op_sel_hi:[0,1]
	v_pk_mul_f32 v[54:55], v[54:55], v[68:69]
	v_pk_mul_f32 v[68:69], v[46:47], v[66:67] op_sel_hi:[1,0]
	v_pk_mul_f32 v[46:47], v[46:47], v[62:63]
	v_exp_f32_e32 v68, v68
	v_exp_f32_e32 v69, v69
	v_pk_add_f32 v[56:57], v[56:57], 1.0 op_sel_hi:[1,0]
	v_lshl_add_u64 v[58:59], v[58:59], 0, v[110:111]
	v_rcp_f32_e32 v56, v56
	v_pk_add_f32 v[68:69], v[68:69], 1.0 op_sel_hi:[1,0]
	v_rcp_f32_e32 v57, v57
	v_rcp_f32_e32 v68, v68
	v_rcp_f32_e32 v69, v69
	v_pk_mul_f32 v[56:57], v[60:61], v[56:57] op_sel_hi:[0,1]
	v_pk_mul_f32 v[56:57], v[72:73], v[56:57]
	v_pk_mul_f32 v[62:63], v[60:61], v[68:69] op_sel_hi:[0,1]
	v_pk_mul_f32 v[62:63], v[46:47], v[62:63]
	v_pk_mul_f32 v[46:47], v[48:49], v[66:67] op_sel_hi:[1,0]
	s_nop 0
	v_exp_f32_e32 v46, v46
	v_exp_f32_e32 v47, v47
	s_nop 0
	v_pk_add_f32 v[46:47], v[46:47], 1.0 op_sel_hi:[1,0]
	s_nop 0
	v_rcp_f32_e32 v46, v46
	v_rcp_f32_e32 v47, v47
	s_nop 0
	v_pk_mul_f32 v[46:47], v[60:61], v[46:47] op_sel_hi:[0,1]
	v_pk_mul_f32 v[60:61], v[64:65], v[46:47]
	v_cvt_pk_bf16_f32 v46, v54, v55
	v_mul_f32_e32 v54, 0xbfb8aa3b, v163
	v_cvt_pk_bf16_f32 v47, v56, v57
	v_pk_mul_f32 v[56:57], v[38:39], v[54:55] op_sel_hi:[1,0]
	v_cvt_pk_bf16_f32 v48, v62, v63
	v_cvt_pk_bf16_f32 v49, v60, v61
	global_store_dwordx4 v[58:59], v[46:49], off
	v_exp_f32_e32 v56, v56
	v_exp_f32_e32 v57, v57
	v_mul_f32_e32 v48, v163, v163
	v_pk_mul_f32 v[38:39], v[38:39], v[50:51]
	v_pk_mul_f32 v[40:41], v[40:41], v[54:55] op_sel_hi:[1,0]
	v_pk_add_f32 v[56:57], v[56:57], 1.0 op_sel_hi:[1,0]
	v_exp_f32_e32 v40, v40
	v_rcp_f32_e32 v56, v56
	v_rcp_f32_e32 v57, v57
	v_exp_f32_e32 v41, v41
	v_add_u32_e32 v46, 0x90, v146
	v_mad_i64_i32 v[46:47], s[10:11], v46, s99, v[148:149]
	v_pk_mul_f32 v[50:51], v[48:49], v[56:57] op_sel_hi:[0,1]
	v_pk_mul_f32 v[38:39], v[38:39], v[50:51]
	v_pk_mul_f32 v[50:51], v[30:31], v[54:55] op_sel_hi:[1,0]
	v_pk_mul_f32 v[30:31], v[30:31], v[42:43]
	v_exp_f32_e32 v50, v50
	v_exp_f32_e32 v51, v51
	v_pk_add_f32 v[40:41], v[40:41], 1.0 op_sel_hi:[1,0]
	v_lshl_add_u64 v[46:47], v[46:47], 0, v[110:111]
	v_rcp_f32_e32 v40, v40
	v_pk_add_f32 v[50:51], v[50:51], 1.0 op_sel_hi:[1,0]
	v_rcp_f32_e32 v41, v41
	v_rcp_f32_e32 v50, v50
	v_rcp_f32_e32 v51, v51
	v_pk_mul_f32 v[40:41], v[48:49], v[40:41] op_sel_hi:[0,1]
	v_pk_mul_f32 v[40:41], v[52:53], v[40:41]
	v_pk_mul_f32 v[42:43], v[48:49], v[50:51] op_sel_hi:[0,1]
	v_pk_mul_f32 v[42:43], v[30:31], v[42:43]
	v_pk_mul_f32 v[30:31], v[32:33], v[54:55] op_sel_hi:[1,0]
	s_nop 0
	v_exp_f32_e32 v30, v30
	v_exp_f32_e32 v31, v31
	s_nop 0
	v_pk_add_f32 v[30:31], v[30:31], 1.0 op_sel_hi:[1,0]
	s_nop 0
	v_rcp_f32_e32 v30, v30
	v_rcp_f32_e32 v31, v31
	s_nop 0
	v_pk_mul_f32 v[30:31], v[48:49], v[30:31] op_sel_hi:[0,1]
	v_pk_mul_f32 v[44:45], v[44:45], v[30:31]
	v_cvt_pk_bf16_f32 v30, v38, v39
	v_mul_f32_e32 v38, 0xbfb8aa3b, v147
	v_cvt_pk_bf16_f32 v31, v40, v41
	v_pk_mul_f32 v[40:41], v[22:23], v[38:39] op_sel_hi:[1,0]
	v_cvt_pk_bf16_f32 v32, v42, v43
	v_cvt_pk_bf16_f32 v33, v44, v45
	global_store_dwordx4 v[46:47], v[30:33], off
	v_exp_f32_e32 v40, v40
	v_exp_f32_e32 v41, v41
	v_mul_f32_e32 v32, v147, v147
	v_pk_mul_f32 v[22:23], v[22:23], v[34:35]
	v_pk_mul_f32 v[24:25], v[24:25], v[38:39] op_sel_hi:[1,0]
	v_pk_add_f32 v[40:41], v[40:41], 1.0 op_sel_hi:[1,0]
	v_exp_f32_e32 v24, v24
	v_rcp_f32_e32 v40, v40
	v_rcp_f32_e32 v41, v41
	v_exp_f32_e32 v25, v25
	v_add_u32_e32 v30, 0xa0, v146
	v_mad_i64_i32 v[30:31], s[10:11], v30, s99, v[148:149]
	v_pk_mul_f32 v[34:35], v[32:33], v[40:41] op_sel_hi:[0,1]
	v_pk_mul_f32 v[22:23], v[22:23], v[34:35]
	v_pk_mul_f32 v[34:35], v[14:15], v[38:39] op_sel_hi:[1,0]
	v_pk_mul_f32 v[14:15], v[14:15], v[26:27]
	v_exp_f32_e32 v34, v34
	v_exp_f32_e32 v35, v35
	v_pk_add_f32 v[24:25], v[24:25], 1.0 op_sel_hi:[1,0]
	v_lshl_add_u64 v[30:31], v[30:31], 0, v[110:111]
	v_rcp_f32_e32 v24, v24
	v_pk_add_f32 v[34:35], v[34:35], 1.0 op_sel_hi:[1,0]
	v_rcp_f32_e32 v25, v25
	v_rcp_f32_e32 v34, v34
	v_rcp_f32_e32 v35, v35
	v_pk_mul_f32 v[24:25], v[32:33], v[24:25] op_sel_hi:[0,1]
	v_pk_mul_f32 v[24:25], v[36:37], v[24:25]
	v_pk_mul_f32 v[26:27], v[32:33], v[34:35] op_sel_hi:[0,1]
	v_pk_mul_f32 v[26:27], v[14:15], v[26:27]
	v_pk_mul_f32 v[14:15], v[16:17], v[38:39] op_sel_hi:[1,0]
	s_nop 0
	v_exp_f32_e32 v14, v14
	v_exp_f32_e32 v15, v15
	s_nop 0
	v_pk_add_f32 v[14:15], v[14:15], 1.0 op_sel_hi:[1,0]
	s_nop 0
	v_rcp_f32_e32 v14, v14
	v_rcp_f32_e32 v15, v15
	s_nop 0
	v_pk_mul_f32 v[14:15], v[32:33], v[14:15] op_sel_hi:[0,1]
	v_pk_mul_f32 v[28:29], v[28:29], v[14:15]
	v_cvt_pk_bf16_f32 v14, v22, v23
	v_cvt_pk_bf16_f32 v15, v24, v25
	v_cvt_pk_bf16_f32 v16, v26, v27
	s_nop 0
	v_cvt_pk_bf16_f32 v17, v28, v29
	global_store_dwordx4 v[30:31], v[14:17], off
	s_nop 1
	v_mul_f32_e32 v16, v0, v0
	v_mul_f32_e32 v0, 0xbfb8aa3b, v0
	v_pk_mul_f32 v[22:23], v[6:7], v[0:1] op_sel_hi:[1,0]
	v_pk_mul_f32 v[6:7], v[6:7], v[18:19]
	v_exp_f32_e32 v22, v22
	v_exp_f32_e32 v23, v23
	v_pk_mul_f32 v[8:9], v[8:9], v[0:1] op_sel_hi:[1,0]
	v_add_u32_e32 v14, 0xb0, v146
	v_exp_f32_e32 v8, v8
	v_pk_add_f32 v[22:23], v[22:23], 1.0 op_sel_hi:[1,0]
	v_exp_f32_e32 v9, v9
	v_rcp_f32_e32 v22, v22
	v_rcp_f32_e32 v23, v23
	v_mad_i64_i32 v[14:15], s[10:11], v14, s99, v[148:149]
	v_pk_add_f32 v[8:9], v[8:9], 1.0 op_sel_hi:[1,0]
	v_pk_mul_f32 v[18:19], v[16:17], v[22:23] op_sel_hi:[0,1]
	v_pk_mul_f32 v[6:7], v[6:7], v[18:19]
	v_pk_mul_f32 v[18:19], v[2:3], v[0:1] op_sel_hi:[1,0]
	v_pk_mul_f32 v[2:3], v[2:3], v[10:11]
	v_exp_f32_e32 v18, v18
	v_exp_f32_e32 v19, v19
	v_rcp_f32_e32 v8, v8
	v_rcp_f32_e32 v9, v9
	v_lshl_add_u64 v[14:15], v[14:15], 0, v[110:111]
	v_pk_add_f32 v[18:19], v[18:19], 1.0 op_sel_hi:[1,0]
	s_mov_b64 s[10:11], -1
	v_rcp_f32_e32 v18, v18
	v_rcp_f32_e32 v19, v19
	v_pk_mul_f32 v[8:9], v[16:17], v[8:9] op_sel_hi:[0,1]
	v_pk_mul_f32 v[8:9], v[20:21], v[8:9]
	v_pk_mul_f32 v[10:11], v[16:17], v[18:19] op_sel_hi:[0,1]
	v_pk_mul_f32 v[10:11], v[2:3], v[10:11]
	v_pk_mul_f32 v[2:3], v[4:5], v[0:1] op_sel_hi:[1,0]
	s_nop 0
	v_exp_f32_e32 v2, v2
	v_exp_f32_e32 v3, v3
	s_nop 0
	v_pk_add_f32 v[2:3], v[2:3], 1.0 op_sel_hi:[1,0]
	s_nop 0
	v_rcp_f32_e32 v2, v2
	v_rcp_f32_e32 v3, v3
	s_nop 0
	v_pk_mul_f32 v[2:3], v[16:17], v[2:3] op_sel_hi:[0,1]
	v_pk_mul_f32 v[12:13], v[12:13], v[2:3]
	v_cvt_pk_bf16_f32 v2, v6, v7
	v_cvt_pk_bf16_f32 v3, v8, v9
	v_cvt_pk_bf16_f32 v4, v10, v11
	s_nop 0
	v_cvt_pk_bf16_f32 v5, v12, v13
	global_store_dwordx4 v[14:15], v[2:5], off
	s_cbranch_vccnz .LBB0_138
	s_nop 0
	v_mov_b32_e32 v2, v1
	v_mov_b32_e32 v3, v1
	v_mov_b32_e32 v0, v1
	v_mov_b64_e32 v[12:13], v[2:3]
	v_mov_b64_e32 v[10:11], v[0:1]
	s_andn2_b64 vcc, exec, s[14:15]
	s_cbranch_vccnz .LBB0_137
	s_barrier
	s_branch .LBB0_137

.LBB0_165:
.LBB0_167:
	s_waitcnt vmcnt(16)
	v_lshl_or_b32 v148, s45, 8, v160
	v_alignbit_b32 v0, v131, v130, 24
	v_and_b32_e32 v147, 0xffffff, v130
	v_cvt_f32_u32_e32 v0, v0
	v_cvt_f32_u32_e32 v147, v147
	v_alignbit_b32 v149, v133, v132, 24
	v_and_b32_e32 v150, 0xffffff, v132
	v_cvt_f32_u32_e32 v149, v149
	v_cvt_f32_u32_e32 v150, v150
	v_fmac_f32_e32 v0, 0x33800000, v147
	v_fmamk_f32 v0, v0, 0x3a000000, v200
	v_rsq_f32_e32 v164, v0
	v_fmac_f32_e32 v149, 0x33800000, v150
	v_fmamk_f32 v0, v149, 0x3a000000, v200
	v_rsq_f32_e32 v166, v0
	v_alignbit_b32 v0, v135, v134, 24
	v_and_b32_e32 v147, 0xffffff, v134
	v_cvt_f32_u32_e32 v0, v0
	v_cvt_f32_u32_e32 v147, v147
	v_alignbit_b32 v149, v137, v136, 24
	v_and_b32_e32 v150, 0xffffff, v136
	v_cvt_f32_u32_e32 v149, v149
	v_cvt_f32_u32_e32 v150, v150
	v_fmac_f32_e32 v0, 0x33800000, v147
	v_fmamk_f32 v0, v0, 0x3a000000, v200
	v_rsq_f32_e32 v168, v0
	v_fmac_f32_e32 v149, 0x33800000, v150
	v_fmamk_f32 v0, v149, 0x3a000000, v200
	v_rsq_f32_e32 v170, v0
	v_alignbit_b32 v0, v139, v138, 24
	v_and_b32_e32 v147, 0xffffff, v138
	v_cvt_f32_u32_e32 v0, v0
	v_cvt_f32_u32_e32 v147, v147
	v_alignbit_b32 v149, v141, v140, 24
	v_and_b32_e32 v150, 0xffffff, v140
	v_cvt_f32_u32_e32 v149, v149
	v_cvt_f32_u32_e32 v150, v150
	v_fmac_f32_e32 v0, 0x33800000, v147
	v_fmamk_f32 v0, v0, 0x3a000000, v200
	v_rsq_f32_e32 v154, v0
	v_fmac_f32_e32 v149, 0x33800000, v150
	v_fmamk_f32 v0, v149, 0x3a000000, v200
	v_rsq_f32_e32 v152, v0
	v_alignbit_b32 v0, v143, v142, 24
	v_and_b32_e32 v147, 0xffffff, v142
	v_cvt_f32_u32_e32 v0, v0
	v_cvt_f32_u32_e32 v147, v147
	v_alignbit_b32 v149, v145, v144, 24
	v_and_b32_e32 v150, 0xffffff, v144
	v_cvt_f32_u32_e32 v149, v149
	v_cvt_f32_u32_e32 v163, v150
	v_fmac_f32_e32 v0, 0x33800000, v147
	v_fmamk_f32 v0, v0, 0x3a000000, v200
	v_rsq_f32_e32 v150, v0
	v_fmac_f32_e32 v149, 0x33800000, v163
	v_fmamk_f32 v0, v149, 0x3a000000, v200
	v_ashrrev_i32_e32 v149, 31, v148
	v_mad_i64_i32 v[172:173], s[10:11], v146, s22, 0
	v_lshl_add_u64 v[172:173], v[172:173], 1, s[16:17]
	v_lshlrev_b64 v[148:149], 1, v[148:149]
	v_pk_mul_f32 v[94:95], v[94:95], v[164:165] op_sel_hi:[1,0]
	v_lshl_add_u64 v[172:173], v[172:173], 0, v[148:149]
	v_pk_mul_f32 v[96:97], v[96:97], v[164:165] op_sel_hi:[1,0]
	v_cvt_pk_bf16_f32 v94, v94, v95
	v_pk_mul_f32 v[100:101], v[100:101], v[164:165] op_sel_hi:[1,0]
	v_cvt_pk_bf16_f32 v95, v96, v97
	v_pk_mul_f32 v[98:99], v[98:99], v[164:165] op_sel_hi:[1,0]
	v_pk_mul_f32 v[62:63], v[62:63], v[166:167] op_sel_hi:[1,0]
	v_cvt_pk_bf16_f32 v96, v98, v99
	v_cvt_pk_bf16_f32 v97, v100, v101
	global_store_dwordx4 v[172:173], v[94:97], off
	v_pk_mul_f32 v[98:99], v[128:129], v[164:165] op_sel_hi:[1,0]
	v_pk_mul_f32 v[100:101], v[126:127], v[164:165] op_sel_hi:[1,0]
	v_pk_mul_f32 v[94:95], v[122:123], v[164:165] op_sel_hi:[1,0]
	v_pk_mul_f32 v[96:97], v[124:125], v[164:165] op_sel_hi:[1,0]
	v_cvt_pk_bf16_f32 v94, v94, v95
	v_pk_mul_f32 v[64:65], v[64:65], v[166:167] op_sel_hi:[1,0]
	v_cvt_pk_bf16_f32 v95, v96, v97
	v_cvt_pk_bf16_f32 v96, v100, v101
	v_cvt_pk_bf16_f32 v97, v98, v99
	global_store_dwordx4 v[172:173], v[94:97], off offset:256
	s_and_b64 vcc, exec, s[18:19]
	s_cbranch_vccz .Lpepi_b
	s_barrier
.Lpepi_b:
	v_cvt_pk_bf16_f32 v62, v62, v63
	v_cvt_pk_bf16_f32 v63, v64, v65
	v_pk_mul_f32 v[76:77], v[76:77], v[166:167] op_sel_hi:[1,0]
	v_pk_mul_f32 v[74:75], v[74:75], v[166:167] op_sel_hi:[1,0]
	v_or_b32_e32 v94, 16, v146
	v_mad_i64_i32 v[94:95], s[10:11], v94, s22, 0
	v_lshl_add_u64 v[94:95], v[94:95], 1, s[16:17]
	v_lshl_add_u64 v[94:95], v[94:95], 0, v[148:149]
	v_cvt_pk_bf16_f32 v64, v74, v75
	v_cvt_pk_bf16_f32 v65, v76, v77
	global_store_dwordx4 v[94:95], v[62:65], off
	v_pk_mul_f32 v[74:75], v[120:121], v[166:167] op_sel_hi:[1,0]
	v_pk_mul_f32 v[76:77], v[118:119], v[166:167] op_sel_hi:[1,0]
	v_pk_mul_f32 v[62:63], v[110:111], v[166:167] op_sel_hi:[1,0]
	v_pk_mul_f32 v[64:65], v[112:113], v[166:167] op_sel_hi:[1,0]
	v_cvt_pk_bf16_f32 v62, v62, v63
	v_pk_mul_f32 v[34:35], v[34:35], v[168:169] op_sel_hi:[1,0]
	v_cvt_pk_bf16_f32 v63, v64, v65
	v_cvt_pk_bf16_f32 v64, v76, v77
	v_cvt_pk_bf16_f32 v65, v74, v75
	global_store_dwordx4 v[94:95], v[62:65], off offset:256
	v_pk_mul_f32 v[36:37], v[36:37], v[168:169] op_sel_hi:[1,0]
	v_cvt_pk_bf16_f32 v34, v34, v35
	v_pk_mul_f32 v[44:45], v[44:45], v[168:169] op_sel_hi:[1,0]
	v_or_b32_e32 v62, 32, v146
	v_mad_i64_i32 v[62:63], s[10:11], v62, s22, 0
	v_lshl_add_u64 v[62:63], v[62:63], 1, s[16:17]
	v_lshl_add_u64 v[62:63], v[62:63], 0, v[148:149]
	v_cvt_pk_bf16_f32 v35, v36, v37
	v_pk_mul_f32 v[42:43], v[42:43], v[168:169] op_sel_hi:[1,0]
	v_pk_mul_f32 v[14:15], v[14:15], v[170:171] op_sel_hi:[1,0]
	v_cvt_pk_bf16_f32 v36, v42, v43
	v_cvt_pk_bf16_f32 v37, v44, v45
	global_store_dwordx4 v[62:63], v[34:37], off
	v_pk_mul_f32 v[42:43], v[104:105], v[168:169] op_sel_hi:[1,0]
	v_pk_mul_f32 v[44:45], v[102:103], v[168:169] op_sel_hi:[1,0]
	v_pk_mul_f32 v[34:35], v[86:87], v[168:169] op_sel_hi:[1,0]
	v_pk_mul_f32 v[36:37], v[88:89], v[168:169] op_sel_hi:[1,0]
	v_cvt_pk_bf16_f32 v34, v34, v35
	v_pk_mul_f32 v[16:17], v[16:17], v[170:171] op_sel_hi:[1,0]
	v_cvt_pk_bf16_f32 v35, v36, v37
	v_cvt_pk_bf16_f32 v36, v44, v45
	v_cvt_pk_bf16_f32 v37, v42, v43
	global_store_dwordx4 v[62:63], v[34:37], off offset:256
	v_cvt_pk_bf16_f32 v14, v14, v15
	v_cvt_pk_bf16_f32 v15, v16, v17
	v_pk_mul_f32 v[24:25], v[24:25], v[170:171] op_sel_hi:[1,0]
	v_pk_mul_f32 v[22:23], v[22:23], v[170:171] op_sel_hi:[1,0]
	v_or_b32_e32 v34, 48, v146
	v_mad_i64_i32 v[34:35], s[10:11], v34, s22, 0
	v_lshl_add_u64 v[34:35], v[34:35], 1, s[16:17]
	v_lshl_add_u64 v[34:35], v[34:35], 0, v[148:149]
	v_cvt_pk_bf16_f32 v16, v22, v23
	v_cvt_pk_bf16_f32 v17, v24, v25
	global_store_dwordx4 v[34:35], v[14:17], off
	v_pk_mul_f32 v[22:23], v[80:81], v[170:171] op_sel_hi:[1,0]
	v_pk_mul_f32 v[24:25], v[78:79], v[170:171] op_sel_hi:[1,0]
	v_pk_mul_f32 v[14:15], v[70:71], v[170:171] op_sel_hi:[1,0]
	v_pk_mul_f32 v[16:17], v[72:73], v[170:171] op_sel_hi:[1,0]
	v_cvt_pk_bf16_f32 v14, v14, v15
	v_pk_mul_f32 v[10:11], v[10:11], v[150:151] op_sel_hi:[1,0]
	v_cvt_pk_bf16_f32 v15, v16, v17
	v_cvt_pk_bf16_f32 v16, v24, v25
	v_cvt_pk_bf16_f32 v17, v22, v23
	global_store_dwordx4 v[34:35], v[14:17], off offset:256
	v_pk_mul_f32 v[24:25], v[68:69], v[154:155] op_sel_hi:[1,0]
	v_pk_mul_f32 v[34:35], v[66:67], v[154:155] op_sel_hi:[1,0]
	v_add_u32_e32 v14, 0x80, v146
	v_mad_i64_i32 v[14:15], s[10:11], v14, s22, 0
	v_lshl_add_u64 v[14:15], v[14:15], 1, s[16:17]
	v_lshl_add_u64 v[22:23], v[14:15], 0, v[148:149]
	v_pk_mul_f32 v[14:15], v[54:55], v[154:155] op_sel_hi:[1,0]
	v_pk_mul_f32 v[16:17], v[56:57], v[154:155] op_sel_hi:[1,0]
	v_cvt_pk_bf16_f32 v14, v14, v15
	v_pk_mul_f32 v[12:13], v[12:13], v[150:151] op_sel_hi:[1,0]
	v_cvt_pk_bf16_f32 v15, v16, v17
	v_cvt_pk_bf16_f32 v16, v34, v35
	v_cvt_pk_bf16_f32 v17, v24, v25
	global_store_dwordx4 v[22:23], v[14:17], off
	v_pk_mul_f32 v[24:25], v[116:117], v[154:155] op_sel_hi:[1,0]
	v_pk_mul_f32 v[34:35], v[114:115], v[154:155] op_sel_hi:[1,0]
	v_pk_mul_f32 v[14:15], v[106:107], v[154:155] op_sel_hi:[1,0]
	v_pk_mul_f32 v[16:17], v[108:109], v[154:155] op_sel_hi:[1,0]
	v_cvt_pk_bf16_f32 v14, v14, v15
	v_rsq_f32_e32 v0, v0
	v_cvt_pk_bf16_f32 v15, v16, v17
	v_cvt_pk_bf16_f32 v16, v34, v35
	v_cvt_pk_bf16_f32 v17, v24, v25
	global_store_dwordx4 v[22:23], v[14:17], off offset:256
	v_pk_mul_f32 v[24:25], v[40:41], v[152:153] op_sel_hi:[1,0]
	v_pk_mul_f32 v[18:19], v[18:19], v[150:151] op_sel_hi:[1,0]
	v_add_u32_e32 v14, 0x90, v146
	v_mad_i64_i32 v[14:15], s[10:11], v14, s22, 0
	v_lshl_add_u64 v[14:15], v[14:15], 1, s[16:17]
	v_lshl_add_u64 v[22:23], v[14:15], 0, v[148:149]
	v_pk_mul_f32 v[14:15], v[30:31], v[152:153] op_sel_hi:[1,0]
	v_pk_mul_f32 v[16:17], v[32:33], v[152:153] op_sel_hi:[1,0]
	v_cvt_pk_bf16_f32 v14, v14, v15
	v_pk_mul_f32 v[30:31], v[38:39], v[152:153] op_sel_hi:[1,0]
	v_cvt_pk_bf16_f32 v15, v16, v17
	v_pk_mul_f32 v[4:5], v[4:5], v[0:1] op_sel_hi:[1,0]
	v_cvt_pk_bf16_f32 v16, v30, v31
	v_cvt_pk_bf16_f32 v17, v24, v25
	global_store_dwordx4 v[22:23], v[14:17], off
	v_pk_mul_f32 v[24:25], v[92:93], v[152:153] op_sel_hi:[1,0]
	v_pk_mul_f32 v[30:31], v[90:91], v[152:153] op_sel_hi:[1,0]
	v_pk_mul_f32 v[14:15], v[82:83], v[152:153] op_sel_hi:[1,0]
	v_pk_mul_f32 v[16:17], v[84:85], v[152:153] op_sel_hi:[1,0]
	v_cvt_pk_bf16_f32 v14, v14, v15
	v_pk_mul_f32 v[2:3], v[2:3], v[0:1] op_sel_hi:[1,0]
	v_cvt_pk_bf16_f32 v15, v16, v17
	v_cvt_pk_bf16_f32 v16, v30, v31
	v_cvt_pk_bf16_f32 v17, v24, v25
	global_store_dwordx4 v[22:23], v[14:17], off offset:256
	v_cvt_pk_bf16_f32 v10, v10, v11
	v_cvt_pk_bf16_f32 v11, v12, v13
	v_cvt_pk_bf16_f32 v12, v18, v19
	v_pk_mul_f32 v[18:19], v[58:59], v[150:151] op_sel_hi:[1,0]
	v_pk_mul_f32 v[8:9], v[8:9], v[0:1] op_sel_hi:[1,0]
	v_add_u32_e32 v14, 0xa0, v146
	v_mad_i64_i32 v[14:15], s[10:11], v14, s22, 0
	v_lshl_add_u64 v[14:15], v[14:15], 1, s[16:17]
	v_lshl_add_u64 v[14:15], v[14:15], 0, v[148:149]
	v_pk_mul_f32 v[16:17], v[20:21], v[150:151] op_sel_hi:[1,0]
	v_pk_mul_f32 v[6:7], v[6:7], v[0:1] op_sel_hi:[1,0]
	v_cvt_pk_bf16_f32 v13, v16, v17
	global_store_dwordx4 v[14:15], v[10:13], off
	v_pk_mul_f32 v[16:17], v[60:61], v[150:151] op_sel_hi:[1,0]
	s_andn2_b64 vcc, exec, s[4:5]
	v_pk_mul_f32 v[10:11], v[46:47], v[150:151] op_sel_hi:[1,0]
	v_pk_mul_f32 v[12:13], v[48:49], v[150:151] op_sel_hi:[1,0]
	v_cvt_pk_bf16_f32 v10, v10, v11
	s_mov_b64 s[4:5], -1
	v_cvt_pk_bf16_f32 v11, v12, v13
	v_cvt_pk_bf16_f32 v12, v18, v19
	v_cvt_pk_bf16_f32 v13, v16, v17
	global_store_dwordx4 v[14:15], v[10:13], off offset:256
	v_cvt_pk_bf16_f32 v2, v2, v3
	v_cvt_pk_bf16_f32 v3, v4, v5
	v_cvt_pk_bf16_f32 v4, v6, v7
	v_cvt_pk_bf16_f32 v5, v8, v9
	v_pk_mul_f32 v[6:7], v[52:53], v[0:1] op_sel_hi:[1,0]
	s_nop 0
	v_add_u32_e32 v10, 0xb0, v146
	v_mad_i64_i32 v[10:11], s[10:11], v10, s22, 0
	v_lshl_add_u64 v[10:11], v[10:11], 1, s[16:17]
	v_lshl_add_u64 v[10:11], v[10:11], 0, v[148:149]
	global_store_dwordx4 v[10:11], v[2:5], off
	v_pk_mul_f32 v[8:9], v[50:51], v[0:1] op_sel_hi:[1,0]
	s_nop 0
	v_pk_mul_f32 v[4:5], v[28:29], v[0:1] op_sel_hi:[1,0]
	v_pk_mul_f32 v[2:3], v[26:27], v[0:1] op_sel_hi:[1,0]
	s_nop 0
	v_cvt_pk_bf16_f32 v2, v2, v3
	v_cvt_pk_bf16_f32 v3, v4, v5
	v_cvt_pk_bf16_f32 v4, v8, v9
	v_cvt_pk_bf16_f32 v5, v6, v7
	global_store_dwordx4 v[10:11], v[2:5], off offset:256
	s_cbranch_vccnz .LBB0_158
	s_nop 0
	v_mov_b32_e32 v2, v1
	v_mov_b32_e32 v3, v1
	v_mov_b32_e32 v0, v1
	v_mov_b64_e32 v[52:53], v[2:3]
	v_mov_b64_e32 v[50:51], v[0:1]
	s_andn2_b64 vcc, exec, s[14:15]
	s_cbranch_vccnz .LBB0_157
	s_barrier
	s_branch .LBB0_157

.LBB0_385:
.LBB0_387:
	s_mov_b64 s[10:11], s[16:17]
	s_waitcnt vmcnt(16)
	v_lshl_add_u32 v196, s22, 8, v211
	s_add_u32 s22, s10, 0x20000
	v_lshl_or_b32 v2, s23, 8, v212
	s_addc_u32 s23, s11, 0
	s_add_u32 s10, s10, 0x30000
	s_addc_u32 s11, s11, 0
	v_lshl_add_u32 v0, v196, 12, v0
	global_load_dwordx4 v[192:195], v0, s[22:23]
	global_load_dwordx4 v[188:191], v0, s[22:23] offset:256
	global_load_dwordx4 v[184:187], v0, s[10:11]
	global_load_dwordx4 v[180:183], v0, s[10:11] offset:256
	s_mov_b64 s[10:11], s[16:17]
	s_add_u32 s22, s10, 0x80000
	s_addc_u32 s23, s11, 0
	s_add_u32 s10, s10, 0x90000
	s_addc_u32 s11, s11, 0
	global_load_dwordx4 v[176:179], v0, s[22:23]
	global_load_dwordx4 v[172:175], v0, s[22:23] offset:256
	global_load_dwordx4 v[168:171], v0, s[10:11]
	global_load_dwordx4 v[164:167], v0, s[10:11] offset:256
	s_mov_b64 s[10:11], s[16:17]
	s_add_u32 s22, s10, 0xa0000
	v_cvt_f32_f16_e32 v218, v4
	v_cvt_f32_f16_sdwa v219, v4 dst_sel:DWORD dst_unused:UNUSED_PAD src0_sel:WORD_1
	s_addc_u32 s23, s11, 0
	v_cvt_f32_f16_e32 v216, v5
	v_cvt_f32_f16_sdwa v217, v5 dst_sel:DWORD dst_unused:UNUSED_PAD src0_sel:WORD_1
	s_add_u32 s10, s10, 0xb0000
	global_load_dwordx4 v[144:147], v0, s[22:23]
	global_load_dwordx4 v[140:143], v0, s[22:23] offset:256
	s_addc_u32 s11, s11, 0
	global_load_dwordx4 v[120:123], v0, s[10:11]
	global_load_dwordx4 v[116:119], v0, s[10:11] offset:256
	s_mov_b32 s10, s27
	s_mov_b64 s[22:23], s[18:19]
	s_mov_b64 s[24:25], s[16:17]
	v_ashrrev_i32_e32 v3, 31, v2
	v_pk_fma_f32 v[160:161], v[160:161], s[10:11], v[218:219] op_sel_hi:[1,0,1]
	v_cvt_f32_f16_e32 v218, v6
	v_cvt_f32_f16_sdwa v219, v6 dst_sel:DWORD dst_unused:UNUSED_PAD src0_sel:WORD_1
	v_pk_fma_f32 v[162:163], v[162:163], s[10:11], v[216:217] op_sel_hi:[1,0,1]
	v_cvt_f32_f16_e32 v216, v7
	v_cvt_f32_f16_sdwa v217, v7 dst_sel:DWORD dst_unused:UNUSED_PAD src0_sel:WORD_1
	v_pk_fma_f32 v[218:219], v[152:153], s[10:11], v[218:219] op_sel_hi:[1,0,1]
	v_cvt_pk_f16_f32 v153, v162, v163
	v_cvt_pk_f16_f32 v152, v160, v161
	v_pk_fma_f32 v[154:155], v[154:155], s[10:11], v[216:217] op_sel_hi:[1,0,1]
	v_cvt_f32_f16_sdwa v0, v153 dst_sel:DWORD dst_unused:UNUSED_PAD src0_sel:WORD_1
	v_cvt_f32_f16_sdwa v160, v152 dst_sel:DWORD dst_unused:UNUSED_PAD src0_sel:WORD_1
	v_cvt_pk_f16_f32 v155, v154, v155
	v_cvt_pk_f16_f32 v154, v218, v219
	v_ashrrev_i32_e32 v197, 31, v196
	v_cvt_f32_f16_sdwa v161, v155 dst_sel:DWORD dst_unused:UNUSED_PAD src0_sel:WORD_1
	v_cvt_f32_f16_sdwa v162, v154 dst_sel:DWORD dst_unused:UNUSED_PAD src0_sel:WORD_1
	v_lshl_add_u64 v[198:199], v[2:3], 1, s[24:25]
	v_lshlrev_b64 v[2:3], 12, v[196:197]
	v_lshl_add_u64 v[2:3], v[198:199], 0, v[2:3]
	v_mul_f32_e32 v160, v160, v160
	v_mul_f32_e32 v0, v0, v0
	global_store_dwordx4 v[2:3], v[152:155], off
	v_fma_mix_f32 v0, v153, v153, v0 op_sel_hi:[1,1,0]
	s_nop 0
	v_fma_mix_f32 v152, v152, v152, v160 op_sel_hi:[1,1,0]
	v_mul_f32_e32 v153, v161, v161
	v_add_f32_e32 v0, v152, v0
	v_mul_f32_e32 v152, v162, v162
	v_fma_mix_f32 v152, v154, v154, v152 op_sel_hi:[1,1,0]
	v_fma_mix_f32 v153, v155, v155, v153 op_sel_hi:[1,1,0]
	v_cvt_f32_f16_e32 v154, v8
	v_add_f32_e32 v152, v152, v153
	v_add_f32_e32 v0, v0, v152
	v_cvt_f32_f16_e32 v152, v9
	v_cvt_f32_f16_sdwa v153, v9 dst_sel:DWORD dst_unused:UNUSED_PAD src0_sel:WORD_1
	v_cvt_f32_f16_sdwa v155, v8 dst_sel:DWORD dst_unused:UNUSED_PAD src0_sel:WORD_1
	v_pk_fma_f32 v[152:153], v[158:159], s[10:11], v[152:153] op_sel_hi:[1,0,1]
	v_cvt_f32_f16_e32 v158, v10
	v_cvt_f32_f16_sdwa v159, v10 dst_sel:DWORD dst_unused:UNUSED_PAD src0_sel:WORD_1
	v_pk_fma_f32 v[154:155], v[156:157], s[10:11], v[154:155] op_sel_hi:[1,0,1]
	v_cvt_f32_f16_e32 v156, v11
	v_cvt_f32_f16_sdwa v157, v11 dst_sel:DWORD dst_unused:UNUSED_PAD src0_sel:WORD_1
	v_pk_fma_f32 v[158:159], v[148:149], s[10:11], v[158:159] op_sel_hi:[1,0,1]
	v_cvt_pk_f16_f32 v149, v152, v153
	v_cvt_pk_f16_f32 v148, v154, v155
	v_pk_fma_f32 v[150:151], v[150:151], s[10:11], v[156:157] op_sel_hi:[1,0,1]
	v_cvt_f32_f16_sdwa v152, v149 dst_sel:DWORD dst_unused:UNUSED_PAD src0_sel:WORD_1
	v_cvt_f32_f16_sdwa v153, v148 dst_sel:DWORD dst_unused:UNUSED_PAD src0_sel:WORD_1
	v_cvt_pk_f16_f32 v151, v150, v151
	v_cvt_pk_f16_f32 v150, v158, v159
	v_cvt_f32_f16_sdwa v155, v150 dst_sel:DWORD dst_unused:UNUSED_PAD src0_sel:WORD_1
	v_cvt_f32_f16_sdwa v154, v151 dst_sel:DWORD dst_unused:UNUSED_PAD src0_sel:WORD_1
	v_mul_f32_e32 v153, v153, v153
	v_mul_f32_e32 v152, v152, v152
	global_store_dwordx4 v[2:3], v[148:151], off offset:256
	s_nop 1
	v_fma_mix_f32 v148, v148, v148, v153 op_sel_hi:[1,1,0]
	v_fma_mix_f32 v149, v149, v149, v152 op_sel_hi:[1,1,0]
	v_mov_b64_e32 v[152:153], 0
	v_add_f32_e32 v148, v148, v149
	v_mul_f32_e32 v149, v155, v155
	v_fma_mix_f32 v149, v150, v150, v149 op_sel_hi:[1,1,0]
	v_mul_f32_e32 v150, v154, v154
	v_fma_mix_f32 v150, v151, v151, v150 op_sel_hi:[1,1,0]
	s_nop 0
	v_add_f32_e32 v149, v149, v150
	v_add_f32_e32 v148, v148, v149
	v_add_f32_e32 v0, v0, v148
	v_mbcnt_lo_u32_b32 v148, -1, 0
	v_mbcnt_hi_u32_b32 v148, -1, v148
	v_mov_b64_e32 v[150:151], 0
	v_lshlrev_b32_e32 v148, 2, v148
	v_xor_b32_e32 v149, 64, v148
	ds_bpermute_b32 v149, v149, v0
	v_xor_b32_e32 v148, 0x80, v148
	s_waitcnt lgkmcnt(0)
	v_add_f32_e32 v0, v0, v149
	ds_bpermute_b32 v154, v148, v0
	v_lshl_add_u64 v[148:149], v[196:197], 3, s[22:23]
	s_and_saveexec_b64 s[22:23], s[6:7]
	s_cbranch_execz .LBB0_389
	s_waitcnt lgkmcnt(0)
	v_add_f32_e32 v152, v0, v154
	v_cvt_i32_f32_e32 v0, v152
	v_cvt_f32_i32_e32 v153, v0
	v_lshlrev_b64 v[154:155], 24, v[0:1]
	v_sub_f32_e32 v152, v152, v153
	v_mul_f32_e32 v152, 0x4b800000, v152
	v_cvt_i32_f32_e32 v152, v152
	v_mov_b32_e32 v153, v1
	v_lshl_add_u64 v[152:153], v[154:155], 0, v[152:153]
	global_atomic_add_x2 v[152:153], v[148:149], v[152:153], off sc0
.LBB0_389:
	s_or_b64 exec, exec, s[22:23]
	s_and_b64 vcc, exec, s[20:21]
	s_cbranch_vccz .Lpepi_r
	s_barrier
.Lpepi_r:
	v_cvt_f32_f16_sdwa v157, v12 dst_sel:DWORD dst_unused:UNUSED_PAD src0_sel:WORD_1
	v_cvt_f32_f16_e32 v156, v12
	v_cvt_f32_f16_sdwa v159, v13 dst_sel:DWORD dst_unused:UNUSED_PAD src0_sel:WORD_1
	v_cvt_f32_f16_e32 v158, v13
	s_mov_b32 s11, s10
	s_mov_b32 s22, s10
	s_mov_b32 s23, s10
	v_pk_fma_f32 v[132:133], v[132:133], s[10:11], v[156:157]
	v_cvt_f32_f16_sdwa v157, v14 dst_sel:DWORD dst_unused:UNUSED_PAD src0_sel:WORD_1
	v_cvt_f32_f16_e32 v156, v14
	v_pk_fma_f32 v[134:135], v[134:135], s[22:23], v[158:159]
	v_cvt_f32_f16_sdwa v159, v15 dst_sel:DWORD dst_unused:UNUSED_PAD src0_sel:WORD_1
	v_cvt_f32_f16_e32 v158, v15
	v_pk_fma_f32 v[156:157], v[124:125], s[10:11], v[156:157]
	v_cvt_pk_f16_f32 v125, v134, v135
	v_cvt_pk_f16_f32 v124, v132, v133
	v_pk_fma_f32 v[126:127], v[126:127], s[22:23], v[158:159]
	v_cvt_f32_f16_sdwa v0, v125 dst_sel:DWORD dst_unused:UNUSED_PAD src0_sel:WORD_1
	v_cvt_f32_f16_sdwa v132, v124 dst_sel:DWORD dst_unused:UNUSED_PAD src0_sel:WORD_1
	s_waitcnt lgkmcnt(0)
	v_or_b32_e32 v154, 16, v196
	v_cvt_pk_f16_f32 v127, v126, v127
	v_cvt_pk_f16_f32 v126, v156, v157
	v_ashrrev_i32_e32 v155, 31, v154
	v_cvt_f32_f16_sdwa v133, v127 dst_sel:DWORD dst_unused:UNUSED_PAD src0_sel:WORD_1
	v_cvt_f32_f16_sdwa v134, v126 dst_sel:DWORD dst_unused:UNUSED_PAD src0_sel:WORD_1
	v_lshlrev_b64 v[154:155], 12, v[154:155]
	v_lshl_add_u64 v[154:155], v[198:199], 0, v[154:155]
	v_mul_f32_e32 v132, v132, v132
	v_mul_f32_e32 v0, v0, v0
	global_store_dwordx4 v[154:155], v[124:127], off
	v_fma_mix_f32 v0, v125, v125, v0 op_sel_hi:[1,1,0]
	v_cvt_f32_f16_sdwa v135, v19 dst_sel:DWORD dst_unused:UNUSED_PAD src0_sel:WORD_1
	v_fma_mix_f32 v124, v124, v124, v132 op_sel_hi:[1,1,0]
	v_mul_f32_e32 v125, v133, v133
	v_add_f32_e32 v0, v124, v0
	v_mul_f32_e32 v124, v134, v134
	v_fma_mix_f32 v124, v126, v126, v124 op_sel_hi:[1,1,0]
	v_fma_mix_f32 v125, v127, v127, v125 op_sel_hi:[1,1,0]
	v_cvt_f32_f16_sdwa v127, v17 dst_sel:DWORD dst_unused:UNUSED_PAD src0_sel:WORD_1
	v_add_f32_e32 v124, v124, v125
	v_add_f32_e32 v0, v0, v124
	v_cvt_f32_f16_sdwa v125, v16 dst_sel:DWORD dst_unused:UNUSED_PAD src0_sel:WORD_1
	v_cvt_f32_f16_e32 v124, v16
	v_cvt_f32_f16_e32 v126, v17
	v_cvt_f32_f16_e32 v134, v19
	v_pk_fma_f32 v[132:133], v[136:137], s[10:11], v[124:125]
	v_cvt_f32_f16_sdwa v125, v18 dst_sel:DWORD dst_unused:UNUSED_PAD src0_sel:WORD_1
	v_cvt_f32_f16_e32 v124, v18
	v_pk_fma_f32 v[126:127], v[138:139], s[22:23], v[126:127]
	v_pk_fma_f32 v[130:131], v[130:131], s[22:23], v[134:135]
	v_pk_fma_f32 v[128:129], v[128:129], s[10:11], v[124:125]
	v_cvt_pk_f16_f32 v125, v126, v127
	v_cvt_pk_f16_f32 v124, v132, v133
	v_cvt_pk_f16_f32 v126, v128, v129
	v_cvt_f32_f16_sdwa v128, v125 dst_sel:DWORD dst_unused:UNUSED_PAD src0_sel:WORD_1
	v_cvt_f32_f16_sdwa v129, v124 dst_sel:DWORD dst_unused:UNUSED_PAD src0_sel:WORD_1
	v_cvt_pk_f16_f32 v127, v130, v131
	v_cvt_f32_f16_sdwa v131, v126 dst_sel:DWORD dst_unused:UNUSED_PAD src0_sel:WORD_1
	v_cvt_f32_f16_sdwa v130, v127 dst_sel:DWORD dst_unused:UNUSED_PAD src0_sel:WORD_1
	v_mul_f32_e32 v129, v129, v129
	v_mul_f32_e32 v128, v128, v128
	global_store_dwordx4 v[154:155], v[124:127], off offset:256
	s_nop 1
	v_fma_mix_f32 v124, v124, v124, v129 op_sel_hi:[1,1,0]
	v_fma_mix_f32 v125, v125, v125, v128 op_sel_hi:[1,1,0]
	s_nop 0
	v_add_f32_e32 v124, v124, v125
	v_mul_f32_e32 v125, v131, v131
	v_fma_mix_f32 v125, v126, v126, v125 op_sel_hi:[1,1,0]
	v_mul_f32_e32 v126, v130, v130
	v_fma_mix_f32 v126, v127, v127, v126 op_sel_hi:[1,1,0]
	s_nop 0
	v_add_f32_e32 v125, v125, v126
	v_add_f32_e32 v124, v124, v125
	v_add_f32_e32 v0, v0, v124
	v_mbcnt_lo_u32_b32 v124, -1, 0
	v_mbcnt_hi_u32_b32 v124, -1, v124
	s_nop 0
	v_lshlrev_b32_e32 v124, 2, v124
	v_xor_b32_e32 v125, 64, v124
	ds_bpermute_b32 v125, v125, v0
	v_xor_b32_e32 v124, 0x80, v124
	s_waitcnt lgkmcnt(0)
	v_add_f32_e32 v0, v0, v125
	ds_bpermute_b32 v124, v124, v0
	s_and_saveexec_b64 s[24:25], s[6:7]
	s_cbranch_execz .LBB0_391
	s_waitcnt lgkmcnt(0)
	v_add_f32_e32 v124, v0, v124
	v_cvt_i32_f32_e32 v0, v124
	v_cvt_f32_i32_e32 v125, v0
	v_lshlrev_b64 v[126:127], 24, v[0:1]
	v_sub_f32_e32 v124, v124, v125
	v_mul_f32_e32 v124, 0x4b800000, v124
	v_cvt_i32_f32_e32 v124, v124
	v_mov_b32_e32 v125, v1
	v_lshl_add_u64 v[124:125], v[126:127], 0, v[124:125]
	global_atomic_add_x2 v[150:151], v[148:149], v[124:125], off offset:128 sc0
